# tail conversion split re-tuned: HGRN waves take 6 of 11 rounds
# speedup vs baseline: 1.0138x; 1.0002x over previous
.LBB0_512:
	v_readlane_b32 s0, v251, 36
	v_readlane_b32 s50, v251, 47
	v_readlane_b32 s1, v251, 37
	v_readlane_b32 s51, v251, 48
	s_and_b64 s[0:1], s[50:51], s[0:1]
	v_readlane_b32 s84, v251, 42
	s_andn2_b64 vcc, exec, s[0:1]
	v_readlane_b32 s60, v251, 40
	v_readlane_b32 s62, v251, 38
	v_readlane_b32 s85, v251, 43
	v_readlane_b32 s61, v251, 41
	v_readlane_b32 s63, v251, 39
	s_cbranch_vccnz .LBB0_539
	s_movk_i32 s93, 0x1800
	s_mov_b32 s94, 0
	s_cmpk_lt_i32 s64, 0x80
	s_cbranch_scc1 .Ltail_hgrn
	s_movk_i32 s93, 0x2c00
	s_movk_i32 s94, 0x1400
	s_branch .Ltail_conv

.LBB0_536:
	s_waitcnt vmcnt(0)
	s_cmpk_gt_i32 s60, 0x17ff
	s_barrier
	s_waitcnt vmcnt(0)
	s_barrier
	s_cbranch_scc1 .LBB0_539
